# chunkB: group-norm partial-sum lane exchanges via v_permlane16/32_swap instead of ds_bpermute
# baseline (speedup 1.0000x reference)
.LBB0_280:
	s_cmp_lg_u32 s20, 0x3e0000
	s_cselect_b32 s15, s39, 31
	s_add_u32 s22, s18, s15
	s_addc_u32 s23, s19, 0
	s_mul_i32 s40, s23, 0x6000
	s_mul_hi_u32 s41, s22, 0x6000
	s_add_i32 s41, s41, s40
	s_mul_i32 s40, s22, 0x6000
	s_add_u32 s40, s86, s40
	s_addc_u32 s41, s87, s41
	s_waitcnt vmcnt(12)
	ds_write_b64 v242, v[182:183]
	ds_write_b64 v242, v[188:189] offset:576
	ds_write_b64 v242, v[184:185] offset:9216
	ds_write_b64 v242, v[190:191] offset:9792
	v_mov_b64_e32 v[226:227], v[10:11]
	s_add_u32 s42, s40, 0x2000
	v_mov_b64_e32 v[224:225], v[8:9]
	s_addc_u32 s43, s41, 0
	v_lshl_add_u64 v[8:9], s[40:41], 0, v[94:95]
	s_lshl_b64 s[40:41], s[22:23], 14
	s_add_u32 s40, s3, s40
	s_addc_u32 s41, s11, s41
	s_lshl_b64 s[22:23], s[22:23], 8
	s_add_u32 s22, s24, s22
	v_mov_b64_e32 v[74:75], v[6:7]
	v_mov_b32_e32 v125, v95
	v_mov_b32_e32 v127, v95
	s_addc_u32 s23, s25, s23
	s_lshl_b32 s15, s15, 6
	v_mov_b64_e32 v[72:73], v[4:5]
	v_mov_b64_e32 v[200:201], v[2:3]
	s_waitcnt vmcnt(11)
	v_mov_b64_e32 v[222:223], v[14:15]
	v_lshl_add_u64 v[4:5], v[8:9], 0, v[124:125]
	v_lshl_add_u64 v[10:11], v[98:99], 2, s[42:43]
	v_lshl_add_u64 v[24:25], v[104:105], 2, s[42:43]
	v_lshl_add_u64 v[8:9], v[8:9], 0, v[126:127]
	s_add_u32 s15, s16, s15
	v_mov_b64_e32 v[198:199], v[0:1]
	v_mov_b64_e32 v[220:221], v[12:13]
	v_mov_b32_e32 v76, v210
	v_mov_b32_e32 v77, v211
	v_mov_b32_e32 v78, v212
	v_mov_b32_e32 v79, v213
	global_load_dwordx4 v[0:3], v[4:5], off
	s_nop 0
	global_load_dwordx4 v[4:7], v[4:5], off offset:1024
	v_lshl_add_u64 v[12:13], v[100:101], 2, s[42:43]
	v_lshl_add_u64 v[14:15], v[102:103], 2, s[42:43]
	global_load_dword v210, v[10:11], off
	global_load_dword v211, v[12:13], off
	global_load_dword v212, v[14:15], off
	global_load_dword v213, v[24:25], off
	s_nop 0
	global_load_dwordx4 v[24:27], v[8:9], off
	global_load_dwordx4 v[28:31], v[8:9], off offset:1024
	v_lshl_add_u64 v[8:9], v[108:109], 2, s[42:43]
	v_mov_b32_e32 v149, v95
	v_or_b32_e32 v48, s15, v96
	v_mov_b64_e32 v[62:63], s[94:95]
	v_lshl_add_u64 v[10:11], v[110:111], 2, s[42:43]
	v_lshl_add_u64 v[12:13], v[112:113], 2, s[42:43]
	v_lshl_add_u64 v[14:15], v[114:115], 2, s[42:43]
	global_load_dword v216, v[8:9], off
	global_load_dword v217, v[10:11], off
	global_load_dword v218, v[12:13], off
	global_load_dword v219, v[14:15], off
	s_addc_u32 s42, s17, 0
	v_lshl_add_u64 v[44:45], s[40:41], 0, v[94:95]
	v_lshl_add_u64 v[8:9], s[40:41], 0, v[148:149]
	v_mad_u64_u32 v[48:49], s[40:41], v48, s35, v[62:63]
	v_mad_i32_i24 v49, s42, v147, v49
	v_mov_b32_e32 v151, v95
	v_or_b32_e32 v64, s15, v106
	v_lshl_add_u64 v[48:49], v[48:49], 0, v[150:151]
	v_mad_u64_u32 v[62:63], s[40:41], v64, s35, v[62:63]
	v_add_co_u32_e32 v50, vcc, s36, v48
	v_mad_i32_i24 v63, s42, v147, v63
	v_lshl_add_u64 v[60:61], v[8:9], 0, s[8:9]
	v_addc_co_u32_e32 v51, vcc, -1, v49, vcc
	v_lshl_add_u64 v[62:63], v[62:63], 0, v[150:151]
	v_lshl_add_u64 v[12:13], v[44:45], 0, v[124:125]
	v_lshl_add_u64 v[46:47], v[60:61], 0, v[124:125]
	v_add_co_u32_e32 v64, vcc, s36, v62
	global_load_dwordx4 v[8:11], v[12:13], off
	s_nop 0
	global_load_dwordx4 v[12:15], v[12:13], off offset:1024
	s_nop 0
	global_load_dwordx2 v[178:179], v[46:47], off
	s_mul_i32 s98, s15, 0x1c00
	s_add_u32 s98, s98, s94
	s_addc_u32 s99, s95, 0
	global_load_dwordx2 v[182:183], v240, s[98:99]
	s_mov_b64 exec, s[100:101]
	global_load_dwordx2 v[186:187], v[50:51], off offset:-1024
	s_mov_b64 exec, -1
	global_load_dwordx2 v[184:185], v240, s[98:99] offset:1280
	v_lshl_add_u64 v[48:49], v[44:45], 0, v[126:127]
	v_lshl_add_u64 v[60:61], v[60:61], 0, v[126:127]
	v_addc_co_u32_e32 v65, vcc, -1, v63, vcc
	global_load_dwordx4 v[44:47], v[48:49], off
	s_nop 0
	global_load_dwordx4 v[48:51], v[48:49], off offset:1024
	s_nop 0
	global_load_dwordx2 v[180:181], v[60:61], off
	global_load_dwordx2 v[188:189], v241, s[98:99]
	s_mov_b64 exec, s[100:101]
	global_load_dwordx2 v[192:193], v[64:65], off offset:-1024
	s_mov_b64 exec, -1
	global_load_dwordx2 v[190:191], v241, s[98:99] offset:1280
	global_load_dword v125, v214, s[22:23]
	global_load_dword v127, v215, s[22:23]
	s_nop 0
	global_load_dwordx4 v[64:67], v[152:153], off
	global_load_dwordx4 v[68:71], v[154:155], off
	global_load_dwordx4 v[60:63], v[156:157], off
	v_cvt_pk_bf16_f32 v80, v16, 0
	v_lshlrev_b32_e32 v81, 16, v80
	v_sub_f32_e32 v16, v16, v81
	v_cvt_pk_bf16_f32 v16, v16, s0
	ds_write_b16 v107, v80
	ds_write_b16 v107, v16 offset:9216
	v_cvt_pk_bf16_f32 v16, v17, 0
	v_lshlrev_b32_e32 v80, 16, v16
	v_sub_f32_e32 v17, v17, v80
	v_cvt_pk_bf16_f32 v17, v17, s0
	ds_write_b16 v107, v16 offset:144
	ds_write_b16 v107, v17 offset:9360
	v_cvt_pk_bf16_f32 v16, v18, 0
	v_lshlrev_b32_e32 v17, 16, v16
	v_sub_f32_e32 v17, v18, v17
	v_cvt_pk_bf16_f32 v17, v17, s0
	ds_write_b16 v107, v16 offset:288
	ds_write_b16 v107, v17 offset:9504
	v_cvt_pk_bf16_f32 v16, v19, 0
	v_lshlrev_b32_e32 v17, 16, v16
	v_sub_f32_e32 v17, v19, v17
	v_cvt_pk_bf16_f32 v17, v17, s0
	ds_write_b16 v107, v16 offset:432
	ds_write_b16 v107, v17 offset:9648
	v_cvt_pk_bf16_f32 v16, v32, 0
	v_lshlrev_b32_e32 v17, 16, v16
	v_sub_f32_e32 v17, v32, v17
	v_cvt_pk_bf16_f32 v17, v17, s0
	ds_write_b16 v135, v16
	ds_write_b16 v135, v17 offset:9216
	v_cvt_pk_bf16_f32 v16, v33, 0
	v_lshlrev_b32_e32 v17, 16, v16
	v_sub_f32_e32 v17, v33, v17
	v_cvt_pk_bf16_f32 v17, v17, s0
	ds_write_b16 v135, v16 offset:144
	ds_write_b16 v135, v17 offset:9360
	v_cvt_pk_bf16_f32 v16, v34, 0
	v_lshlrev_b32_e32 v17, 16, v16
	v_sub_f32_e32 v17, v34, v17
	v_cvt_pk_bf16_f32 v17, v17, s0
	ds_write_b16 v135, v16 offset:288
	ds_write_b16 v135, v17 offset:9504
	v_cvt_pk_bf16_f32 v16, v35, 0
	v_lshlrev_b32_e32 v17, 16, v16
	v_sub_f32_e32 v17, v35, v17
	v_cvt_pk_bf16_f32 v17, v17, s0
	ds_write_b16 v135, v16 offset:432
	ds_write_b16 v135, v17 offset:9648
	s_waitcnt lgkmcnt(0)
	s_barrier
	ds_read_b128 v[80:83], v139
	ds_read_b128 v[32:35], v139 offset:64
	s_waitcnt lgkmcnt(1)
	v_mfma_f32_16x16x32_bf16 v[16:19], v[80:83], v[198:201], v[76:79]
	ds_read_b128 v[84:87], v139 offset:9216
	s_nop 1
	ds_read_b128 v[76:79], v139 offset:9280
	s_waitcnt vmcnt(39)
	v_lshlrev_b32_e32 v202, 16, v196
	v_and_b32_e32 v203, 0xffff0000, v196
	s_waitcnt lgkmcnt(1)
	v_mfma_f32_16x16x32_bf16 v[16:19], v[84:87], v[198:201], v[16:19]
	v_lshlrev_b32_e32 v196, 16, v197
	v_and_b32_e32 v197, 0xffff0000, v197
	v_and_b32_e32 v151, 64, v209
	v_mfma_f32_16x16x32_bf16 v[198:201], v[80:83], v[224:227], 0
	v_xor_b32_e32 v149, 16, v209
	v_add_u32_e32 v151, 64, v151
	v_cmp_lt_i32_e32 vcc, v149, v151
	v_mfma_f32_16x16x32_bf16 v[198:201], v[32:35], v[220:223], v[198:201]
	v_xor_b32_e32 v224, 32, v209
	v_cndmask_b32_e32 v149, v209, v149, vcc
	v_lshlrev_b32_e32 v149, 2, v149
	v_cmp_lt_i32_e32 vcc, v224, v151
	v_mfma_f32_16x16x32_bf16 v[16:19], v[32:35], v[72:75], v[16:19]
	s_nop 2
	v_add_f32_e64 v198, v198, v202
	v_add_f32_e64 v199, v199, v203
	v_pk_add_f32 v[196:197], v[200:201], v[196:197]
	v_pk_mul_f32 v[200:201], v[198:199], v[198:199]
	v_pk_mul_f32 v[202:203], v[196:197], v[196:197]
	v_mov_b32_e32 v220, v198
	v_mov_b32_e32 v221, v200
	v_mov_b32_e32 v200, v199
	v_pk_add_f32 v[200:201], v[220:221], v[200:201]
	v_mov_b32_e32 v220, v196
	v_mov_b32_e32 v221, v202
	v_mov_b32_e32 v202, v197
	v_pk_add_f32 v[202:203], v[220:221], v[202:203]
	v_cndmask_b32_e32 v151, v209, v224, vcc
	v_pk_add_f32 v[200:201], v[200:201], v[202:203]
	v_mov_b32_e32 v202, v200
	v_mov_b32_e32 v203, v201
	s_nop 1
	v_permlane16_swap_b32 v200, v202
	v_permlane16_swap_b32 v201, v203
	v_lshlrev_b32_e32 v151, 2, v151
	s_waitcnt lgkmcnt(0)
	v_mfma_f32_16x16x32_bf16 v[16:19], v[76:79], v[72:75], v[16:19]
	s_waitcnt lgkmcnt(0)
	v_pk_add_f32 v[200:201], v[200:201], v[202:203]
	v_mov_b32_e32 v202, v200
	v_mov_b32_e32 v203, v201
	s_nop 1
	v_permlane32_swap_b32 v200, v202
	v_permlane32_swap_b32 v201, v203
	s_and_saveexec_b64 s[22:23], s[30:31]
	s_cbranch_execz .LBB0_282
	s_waitcnt lgkmcnt(0)
	v_pk_add_f32 v[72:73], v[200:201], v[202:203]
	v_add_u32_e32 v74, s26, v130
	ds_write_b64 v74, v[72:73] offset:18432
.LBB0_282:
	s_or_b64 exec, exec, s[22:23]
	s_waitcnt vmcnt(35)
	v_mfma_f32_16x16x32_bf16 v[56:59], v[80:83], v[56:59], 0
	s_waitcnt vmcnt(33)
	v_lshlrev_b32_e32 v72, 16, v194
	v_and_b32_e32 v73, 0xffff0000, v194
	v_lshlrev_b32_e32 v74, 16, v195
	v_mfma_f32_16x16x32_bf16 v[54:57], v[32:35], v[52:55], v[56:59]
	v_and_b32_e32 v75, 0xffff0000, v195
	v_mfma_f32_16x16x32_bf16 v[40:43], v[80:83], v[36:39], v[40:43]
	v_mfma_f32_16x16x32_bf16 v[36:39], v[84:87], v[36:39], v[40:43]
	s_nop 4
	v_add_f32_e64 v54, v54, v72
	v_add_f32_e64 v55, v55, v73
	v_pk_add_f32 v[52:53], v[56:57], v[74:75]
	v_pk_mul_f32 v[56:57], v[54:55], v[54:55]
	v_pk_mul_f32 v[58:59], v[52:53], v[52:53]
	v_mov_b32_e32 v72, v54
	v_mov_b32_e32 v73, v56
	v_mov_b32_e32 v56, v55
	v_mov_b32_e32 v42, v52
	v_mov_b32_e32 v43, v58
	v_mov_b32_e32 v58, v53
	v_pk_add_f32 v[40:41], v[72:73], v[56:57]
	v_pk_add_f32 v[42:43], v[42:43], v[58:59]
	v_mfma_f32_16x16x32_bf16 v[32:35], v[32:35], v[20:23], v[36:39]
	v_add_f32_e64 v40, v40, v42
	v_add_f32_e64 v41, v41, v43
	v_mov_b32_e32 v42, v40
	v_mov_b32_e32 v43, v41
	s_nop 1
	v_permlane16_swap_b32 v40, v42
	v_permlane16_swap_b32 v41, v43
	v_mfma_f32_16x16x32_bf16 v[32:35], v[76:79], v[20:23], v[32:35]
	s_waitcnt lgkmcnt(0)
	v_pk_add_f32 v[36:37], v[40:41], v[42:43]
	v_mov_b32_e32 v38, v36
	v_mov_b32_e32 v39, v37
	s_nop 1
	v_permlane32_swap_b32 v36, v38
	v_permlane32_swap_b32 v37, v39
	ds_read_b64 v[174:175], v243
	ds_read_b64 v[168:169], v243 offset:2304
	ds_read_b64 v[176:177], v243 offset:9216
	ds_read_b64 v[166:167], v243 offset:11520
	s_and_saveexec_b64 s[22:23], s[30:31]
	s_cbranch_execz .LBB0_279
	s_waitcnt lgkmcnt(0)
	v_pk_add_f32 v[20:21], v[36:37], v[38:39]
	v_add_u32_e32 v22, s27, v130
	ds_write_b64 v22, v[20:21] offset:18432
	s_branch .LBB0_279
